# differential attention: merged write waits, key counter only in the last pair, next queue item popped inside the last tile pair
# baseline (speedup 1.0000x reference)
; template <bool DIFF>
; __device__ __forceinline__ void attn_unit(CA& A, int l, int b, int hh, int qb, LAS unsigned char* lds, float lam, float lam_init) {
;     ...
;         if (has_next) { ATT_LOAD(DIFF ? t + 1 : t - 1); if (!DIFF) nc_hi = ncp[key0 - 1]; }
;         if (key0 <= qlast) {
;             const LAS unsigned char* Kb = lds + AL_KS + buf * AL_KSZ;
;             const LAS unsigned char* Vb = lds + AL_VT + buf * AL_VSZ;
;             f32x16 p[2];
; #pragma unroll
;             for (int kt = 0; kt < 2; ++kt) {
;                 if (!DIFF) {
;                     const LAS float* nc = (const LAS float*)(lds + AL_NC + buf * 512) + 32 * kt + 4 * hi;
; #pragma unroll
;                     for (int g = 0; g < 4; ++g) { const f32x4 c4 = *(const LAS f32x4*)(nc + 8 * g); p[kt][4 * g] = c4[0]; p[kt][4 * g + 1] = c4[1]; p[kt][4 * g + 2] = c4[2]; p[kt][4 * g + 3] = c4[3]; }
;                 }
; #pragma unroll
;                 for (int s = 0; s < NS; ++s) {
;                     const bf16x8 a = *(const LAS bf16x8*)(Kb + (32 * kt + r32) * 144 + (koff + 16 * s + 8 * hi) * 2);
;                     if (DIFF && s == 0) p[kt] = __builtin_amdgcn_mfma_f32_32x32x16_bf16(a, qf[s], negm, 0, 0, 0);
;                     else p[kt] = __builtin_amdgcn_mfma_f32_32x32x16_bf16(a, qf[s], p[kt], 0, 0, 0);
;                 }
;             }
;             if (!DIFF) {
; #pragma unroll
;                 for (int kt = 0; kt < 2; ++kt)
; #pragma unroll
;                     for (int r = 0; r < 16; ++r) p[kt][r] -= m_ref;
;             }
;             if (key0 + 63 > qfirst) {
; #pragma unroll
;                 for (int kt = 0; kt < 2; ++kt)
; #pragma unroll
;                     for (int r = 0; r < 16; ++r) if (key0 + 32 * kt + crow(r, hi) > qmine) p[kt][r] = -1e30f;
;             }
;             first = false;
; #pragma unroll
;             for (int kt = 0; kt < 2; ++kt)
; #pragma unroll
;                 for (int r = 0; r < 16; ++r) p[kt][r] = __builtin_amdgcn_exp2f(p[kt][r]);
;             bf16x8 pb[2][2];
; #pragma unroll
;             for (int kt = 0; kt < 2; ++kt)
; #pragma unroll
;                 for (int i = 0; i < 2; ++i) { v4u w;
; #pragma unroll
;                     for (int j = 0; j < 4; ++j) w[j] = pk2(p[kt][8 * i + 2 * j], p[kt][8 * i + 2 * j + 1]);
;                     pb[kt][i] = __builtin_bit_cast(bf16x8, w); }
; #pragma unroll
.LBB0_741:
	global_load_dwordx4 v[120:123], v[134:135], off
	global_load_dwordx4 v[124:127], v[132:133], off
	ds_read_b128 v[148:151], v200
	ds_read_b128 v[152:155], v201
	ds_read_b128 v[156:159], v200 offset:32
	ds_read_b128 v[160:163], v201 offset:32
	s_waitcnt lgkmcnt(2)
	v_mfma_f32_32x32x16_bf16 v[96:111], v[148:151], v[112:115], v[48:63]
	v_mfma_f32_32x32x16_bf16 v[80:95], v[152:155], v[112:115], v[48:63]
	s_waitcnt lgkmcnt(0)
	v_mfma_f32_32x32x16_bf16 v[96:111], v[156:159], v[116:119], v[96:111]
	v_mfma_f32_32x32x16_bf16 v[80:95], v[160:163], v[116:119], v[80:95]
	ds_read2_b64 v[164:167], v202 offset0:0 offset1:2
	ds_read2_b64 v[168:171], v203 offset0:32 offset1:34
	ds_read2_b64 v[172:175], v202 offset0:4 offset1:6
	ds_read2_b64 v[180:183], v203 offset0:36 offset1:38
	ds_read2_b64 v[184:187], v202 offset0:8 offset1:10
	ds_read2_b64 v[188:191], v203 offset0:40 offset1:42
	ds_read2_b64 v[192:195], v202 offset0:12 offset1:14
	ds_read2_b64 v[196:199], v203 offset0:44 offset1:46
	s_nop 2
	v_exp_f32_e32 v96, v96
	v_exp_f32_e32 v97, v97
	v_exp_f32_e32 v98, v98
	v_exp_f32_e32 v99, v99
	v_exp_f32_e32 v100, v100
	v_exp_f32_e32 v101, v101
	v_exp_f32_e32 v102, v102
	v_exp_f32_e32 v103, v103
	v_cvt_pk_bf16_f32 v6, v96, v97
	v_cvt_pk_bf16_f32 v7, v98, v99
	v_cvt_pk_bf16_f32 v8, v100, v101
	v_cvt_pk_bf16_f32 v9, v102, v103
	v_exp_f32_e32 v104, v104
	v_exp_f32_e32 v105, v105
	s_waitcnt lgkmcnt(6)
	v_mfma_f32_32x32x16_bf16 v[32:47], v[164:167], v[6:9], v[32:47]
	v_exp_f32_e32 v106, v106
	v_exp_f32_e32 v107, v107
	v_cvt_pk_bf16_f32 v208, v104, v105
	v_mfma_f32_32x32x16_bf16 v[16:31], v[168:171], v[6:9], v[16:31]
	v_exp_f32_e32 v108, v108
	v_exp_f32_e32 v109, v109
	v_cvt_pk_bf16_f32 v209, v106, v107
	v_mfma_f32_32x32x16_bf16 v[64:79], v[204:207], v[6:9], v[64:79]
	v_exp_f32_e32 v110, v110
	v_exp_f32_e32 v111, v111
	v_cvt_pk_bf16_f32 v210, v108, v109
	v_exp_f32_e32 v80, v80
	v_cvt_pk_bf16_f32 v211, v110, v111
	v_exp_f32_e32 v81, v81
	s_waitcnt lgkmcnt(4)
	v_mfma_f32_32x32x16_bf16 v[32:47], v[172:175], v[208:211], v[32:47]
	v_exp_f32_e32 v82, v82
	v_exp_f32_e32 v83, v83
	v_cvt_pk_bf16_f32 v6, v80, v81
	v_mfma_f32_32x32x16_bf16 v[16:31], v[180:183], v[208:211], v[16:31]
	v_exp_f32_e32 v84, v84
	v_exp_f32_e32 v85, v85
	v_cvt_pk_bf16_f32 v7, v82, v83
	v_mfma_f32_32x32x16_bf16 v[64:79], v[204:207], v[208:211], v[64:79]
	v_exp_f32_e32 v86, v86
	v_exp_f32_e32 v87, v87
	v_cvt_pk_bf16_f32 v8, v84, v85
	v_exp_f32_e32 v88, v88
	v_cvt_pk_bf16_f32 v9, v86, v87
	v_exp_f32_e32 v89, v89
	s_waitcnt lgkmcnt(2)
	v_mfma_f32_32x32x16_bf16 v[32:47], v[184:187], v[6:9], v[32:47]
	v_exp_f32_e32 v90, v90
	v_exp_f32_e32 v91, v91
	v_cvt_pk_bf16_f32 v208, v88, v89
	v_mfma_f32_32x32x16_bf16 v[16:31], v[188:191], v[6:9], v[16:31]
	v_exp_f32_e32 v92, v92
	v_exp_f32_e32 v93, v93
	v_cvt_pk_bf16_f32 v209, v90, v91
	v_mfma_f32_32x32x16_bf16 v[64:79], v[204:207], v[6:9], v[64:79]
	v_exp_f32_e32 v94, v94
	v_exp_f32_e32 v95, v95
	v_cvt_pk_bf16_f32 v210, v92, v93
	s_nop 0
	v_cvt_pk_bf16_f32 v211, v94, v95
	s_waitcnt lgkmcnt(0)
	s_nop 0
	v_mfma_f32_32x32x16_bf16 v[32:47], v[192:195], v[208:211], v[32:47]
	v_mfma_f32_32x32x16_bf16 v[16:31], v[196:199], v[208:211], v[16:31]
	v_mfma_f32_32x32x16_bf16 v[64:79], v[204:207], v[208:211], v[64:79]
	s_waitcnt vmcnt(0)
	ds_write_b128 v139, v[120:123] offset:9216
	ds_write_b16 v140, v124 offset:27136
	ds_write_b16_d16_hi v140, v124 offset:27272
	ds_write_b16 v140, v125 offset:27408
	ds_write_b16_d16_hi v140, v125 offset:27544
	ds_write_b16 v140, v126 offset:27680
	ds_write_b16_d16_hi v140, v126 offset:27816
	ds_write_b16 v140, v127 offset:27952
	ds_write_b16_d16_hi v140, v127 offset:28088
	v_lshl_add_u64 v[132:133], v[132:133], 0, s[4:5]
	v_lshl_add_u64 v[134:135], v[134:135], 0, s[4:5]
	s_waitcnt lgkmcnt(0)
	s_barrier
	global_load_dwordx4 v[120:123], v[134:135], off
	global_load_dwordx4 v[124:127], v[132:133], off
	ds_read_b128 v[148:151], v200 offset:9216
	ds_read_b128 v[152:155], v201 offset:9216
	ds_read_b128 v[156:159], v200 offset:9248
	ds_read_b128 v[160:163], v201 offset:9248
	s_waitcnt lgkmcnt(2)
	v_mfma_f32_32x32x16_bf16 v[96:111], v[148:151], v[112:115], v[48:63]
	v_mfma_f32_32x32x16_bf16 v[80:95], v[152:155], v[112:115], v[48:63]
	s_waitcnt lgkmcnt(0)
	v_mfma_f32_32x32x16_bf16 v[96:111], v[156:159], v[116:119], v[96:111]
	v_mfma_f32_32x32x16_bf16 v[80:95], v[160:163], v[116:119], v[80:95]
	ds_read2_b64 v[164:167], v212 offset0:0 offset1:2
	ds_read2_b64 v[168:171], v213 offset0:32 offset1:34
	ds_read2_b64 v[172:175], v212 offset0:4 offset1:6
	ds_read2_b64 v[180:183], v213 offset0:36 offset1:38
	ds_read2_b64 v[184:187], v212 offset0:8 offset1:10
	ds_read2_b64 v[188:191], v213 offset0:40 offset1:42
	ds_read2_b64 v[192:195], v212 offset0:12 offset1:14
	ds_read2_b64 v[196:199], v213 offset0:44 offset1:46
	s_nop 2
	v_exp_f32_e32 v96, v96
	v_exp_f32_e32 v97, v97
	v_exp_f32_e32 v98, v98
	v_exp_f32_e32 v99, v99
	v_exp_f32_e32 v100, v100
	v_exp_f32_e32 v101, v101
	v_exp_f32_e32 v102, v102
	v_exp_f32_e32 v103, v103
	v_cvt_pk_bf16_f32 v6, v96, v97
	v_cvt_pk_bf16_f32 v7, v98, v99
	v_cvt_pk_bf16_f32 v8, v100, v101
	v_cvt_pk_bf16_f32 v9, v102, v103
	v_exp_f32_e32 v104, v104
	v_exp_f32_e32 v105, v105
	s_waitcnt lgkmcnt(6)
	v_mfma_f32_32x32x16_bf16 v[32:47], v[164:167], v[6:9], v[32:47]
	v_exp_f32_e32 v106, v106
	v_exp_f32_e32 v107, v107
	v_cvt_pk_bf16_f32 v208, v104, v105
	v_mfma_f32_32x32x16_bf16 v[16:31], v[168:171], v[6:9], v[16:31]
	v_exp_f32_e32 v108, v108
	v_exp_f32_e32 v109, v109
	v_cvt_pk_bf16_f32 v209, v106, v107
	v_mfma_f32_32x32x16_bf16 v[64:79], v[204:207], v[6:9], v[64:79]
	v_exp_f32_e32 v110, v110
	v_exp_f32_e32 v111, v111
	v_cvt_pk_bf16_f32 v210, v108, v109
	v_exp_f32_e32 v80, v80
	v_cvt_pk_bf16_f32 v211, v110, v111
	v_exp_f32_e32 v81, v81
	s_waitcnt lgkmcnt(4)
; #define LAS __attribute__((address_space(3)))
; __device__ __forceinline__ int crow(int r, int hi) { return (r & 3) + 8 * (r >> 2) + 4 * hi; }
; #define ATT_LOAD(t) do { kraw = *(const v4u*)(kp + (size_t)(t) * 64 * ZC); vraw = *(const v4u*)(vp + (size_t)(t) * 64 * ZC); \
;         if (!DIFF && tid < 64) ncv = ncp[(t) * 64 + tid]; } while (0)
; template <bool DIFF>
; __device__ __forceinline__ void attn_unit(CA& A, int l, int b, int hh, int qb, LAS unsigned char* lds, float lam, float lam_init) {
;     ...
;         if (has_next) { ATT_LOAD(DIFF ? t + 1 : t - 1); if (!DIFF) nc_hi = ncp[key0 - 1]; }
;         if (key0 <= qlast) {
;             const LAS unsigned char* Kb = lds + AL_KS + buf * AL_KSZ;
;             const LAS unsigned char* Vb = lds + AL_VT + buf * AL_VSZ;
;             f32x16 p[2];
; #pragma unroll
;             for (int kt = 0; kt < 2; ++kt) {
;                 if (!DIFF) {
;                     const LAS float* nc = (const LAS float*)(lds + AL_NC + buf * 512) + 32 * kt + 4 * hi;
; #pragma unroll
;                     for (int g = 0; g < 4; ++g) { const f32x4 c4 = *(const LAS f32x4*)(nc + 8 * g); p[kt][4 * g] = c4[0]; p[kt][4 * g + 1] = c4[1]; p[kt][4 * g + 2] = c4[2]; p[kt][4 * g + 3] = c4[3]; }
;                 }
; #pragma unroll
;                 for (int s = 0; s < NS; ++s) {
;                     const bf16x8 a = *(const LAS bf16x8*)(Kb + (32 * kt + r32) * 144 + (koff + 16 * s + 8 * hi) * 2);
;                     if (DIFF && s == 0) p[kt] = __builtin_amdgcn_mfma_f32_32x32x16_bf16(a, qf[s], negm, 0, 0, 0);
;                     else p[kt] = __builtin_amdgcn_mfma_f32_32x32x16_bf16(a, qf[s], p[kt], 0, 0, 0);
;                 }
;             }
;             if (!DIFF) {
; #pragma unroll
;                 for (int kt = 0; kt < 2; ++kt)
; #pragma unroll
;                     for (int r = 0; r < 16; ++r) p[kt][r] -= m_ref;
;             }
;             if (key0 + 63 > qfirst) {
; #pragma unroll
;                 for (int kt = 0; kt < 2; ++kt)
; #pragma unroll
;                     for (int r = 0; r < 16; ++r) if (key0 + 32 * kt + crow(r, hi) > qmine) p[kt][r] = -1e30f;
;             }
	v_mfma_f32_32x32x16_bf16 v[32:47], v[172:175], v[208:211], v[32:47]
	v_exp_f32_e32 v82, v82
	v_exp_f32_e32 v83, v83
	v_cvt_pk_bf16_f32 v6, v80, v81
	v_mfma_f32_32x32x16_bf16 v[16:31], v[180:183], v[208:211], v[16:31]
	v_exp_f32_e32 v84, v84
	v_exp_f32_e32 v85, v85
	v_cvt_pk_bf16_f32 v7, v82, v83
	v_mfma_f32_32x32x16_bf16 v[64:79], v[204:207], v[208:211], v[64:79]
	v_exp_f32_e32 v86, v86
	v_exp_f32_e32 v87, v87
	v_cvt_pk_bf16_f32 v8, v84, v85
	v_exp_f32_e32 v88, v88
	v_cvt_pk_bf16_f32 v9, v86, v87
	v_exp_f32_e32 v89, v89
	s_waitcnt lgkmcnt(2)
	v_mfma_f32_32x32x16_bf16 v[32:47], v[184:187], v[6:9], v[32:47]
	v_exp_f32_e32 v90, v90
	v_exp_f32_e32 v91, v91
	v_cvt_pk_bf16_f32 v208, v88, v89
	v_mfma_f32_32x32x16_bf16 v[16:31], v[188:191], v[6:9], v[16:31]
	v_exp_f32_e32 v92, v92
	v_exp_f32_e32 v93, v93
	v_cvt_pk_bf16_f32 v209, v90, v91
	v_mfma_f32_32x32x16_bf16 v[64:79], v[204:207], v[6:9], v[64:79]
	v_exp_f32_e32 v94, v94
	v_exp_f32_e32 v95, v95
	v_cvt_pk_bf16_f32 v210, v92, v93
	s_nop 0
	v_cvt_pk_bf16_f32 v211, v94, v95
	s_waitcnt lgkmcnt(0)
	s_nop 0
	v_mfma_f32_32x32x16_bf16 v[32:47], v[192:195], v[208:211], v[32:47]
	v_mfma_f32_32x32x16_bf16 v[16:31], v[196:199], v[208:211], v[16:31]
	v_mfma_f32_32x32x16_bf16 v[64:79], v[204:207], v[208:211], v[64:79]
	s_waitcnt vmcnt(0)
	ds_write_b128 v139, v[120:123]
	ds_write_b16 v140, v124 offset:18432
	ds_write_b16_d16_hi v140, v124 offset:18568
	ds_write_b16 v140, v125 offset:18704
	ds_write_b16_d16_hi v140, v125 offset:18840
	ds_write_b16 v140, v126 offset:18976
	ds_write_b16_d16_hi v140, v126 offset:19112
	ds_write_b16 v140, v127 offset:19248
	ds_write_b16_d16_hi v140, v127 offset:19384
	v_lshl_add_u64 v[132:133], v[132:133], 0, s[4:5]
	v_lshl_add_u64 v[134:135], v[134:135], 0, s[4:5]
	s_add_i32 s31, s31, 2
	s_cmp_lt_u32 s31, s29
	s_waitcnt lgkmcnt(0)
	s_barrier
	s_cbranch_scc1 .LBB0_741
.Lmy_d_final:
	s_lshl_b32 s26, s29, 6
	s_add_i32 s26, s26, 63
	global_load_dwordx4 v[120:123], v[134:135], off
	global_load_dwordx4 v[124:127], v[132:133], off
	ds_read_b128 v[148:151], v200
	ds_read_b128 v[152:155], v201
	ds_read_b128 v[156:159], v200 offset:32
	ds_read_b128 v[160:163], v201 offset:32
	s_waitcnt lgkmcnt(2)
	v_mfma_f32_32x32x16_bf16 v[96:111], v[148:151], v[112:115], v[48:63]
	v_mfma_f32_32x32x16_bf16 v[80:95], v[152:155], v[112:115], v[48:63]
	s_waitcnt lgkmcnt(0)
	v_mfma_f32_32x32x16_bf16 v[96:111], v[156:159], v[116:119], v[96:111]
	v_mfma_f32_32x32x16_bf16 v[80:95], v[160:163], v[116:119], v[80:95]
	ds_read2_b64 v[164:167], v202 offset0:0 offset1:2
	ds_read2_b64 v[168:171], v203 offset0:32 offset1:34
	ds_read2_b64 v[172:175], v202 offset0:4 offset1:6
	ds_read2_b64 v[180:183], v203 offset0:36 offset1:38
	ds_read2_b64 v[184:187], v202 offset0:8 offset1:10
	ds_read2_b64 v[188:191], v203 offset0:40 offset1:42
	ds_read2_b64 v[192:195], v202 offset0:12 offset1:14
	ds_read2_b64 v[196:199], v203 offset0:44 offset1:46
	s_cmp_le_u32 s26, s25
	s_nop 1
	s_cbranch_scc1 .Lmy_df0_pv
	v_add_u32_e32 v1, s26, v131
	v_subrev_u32_e32 v2, 63, v1
	v_cmp_gt_u32_e32 vcc, v2, v138
	s_nop 1
	v_cndmask_b32_e32 v3, v96, v225, vcc
	v_cmp_lt_u32_e32 vcc, v2, v138
	v_subrev_u32_e32 v2, 61, v1
	s_nop 0
	v_cndmask_b32_e32 v96, v3, v96, vcc
	v_cndmask_b32_e32 v97, v225, v97, vcc
	v_cmp_le_u32_e32 vcc, v2, v138
	v_subrev_u32_e32 v2, 60, v1
	s_nop 0
	v_cndmask_b32_e32 v98, v225, v98, vcc
	v_cmp_le_u32_e32 vcc, v2, v138
	v_subrev_u32_e32 v2, 55, v1
	s_nop 0
	v_cndmask_b32_e32 v99, v225, v99, vcc
	v_cmp_le_u32_e32 vcc, v2, v138
	v_subrev_u32_e32 v2, 54, v1
	s_nop 0
	v_cndmask_b32_e32 v100, v225, v100, vcc
	v_cmp_le_u32_e32 vcc, v2, v138
	v_subrev_u32_e32 v2, 53, v1
	s_nop 0
	v_cndmask_b32_e32 v101, v225, v101, vcc
	v_cmp_le_u32_e32 vcc, v2, v138
	v_subrev_u32_e32 v2, 52, v1
	s_nop 0
	v_cndmask_b32_e32 v102, v225, v102, vcc
	v_cmp_le_u32_e32 vcc, v2, v138
	v_subrev_u32_e32 v2, 47, v1
	s_nop 0
	v_cndmask_b32_e32 v103, v225, v103, vcc
	v_cmp_le_u32_e32 vcc, v2, v138
	v_subrev_u32_e32 v2, 46, v1
	s_nop 0
	v_cndmask_b32_e32 v104, v225, v104, vcc
	v_cmp_le_u32_e32 vcc, v2, v138
	v_subrev_u32_e32 v2, 45, v1
	s_nop 0
	v_cndmask_b32_e32 v105, v225, v105, vcc
	v_cmp_le_u32_e32 vcc, v2, v138
	v_subrev_u32_e32 v2, 44, v1
	s_nop 0
	v_cndmask_b32_e32 v106, v225, v106, vcc
	v_cmp_le_u32_e32 vcc, v2, v138
	v_subrev_u32_e32 v2, 39, v1
	s_nop 0
	v_cndmask_b32_e32 v107, v225, v107, vcc
	v_cmp_le_u32_e32 vcc, v2, v138
	v_subrev_u32_e32 v2, 38, v1
	s_nop 0
	v_cndmask_b32_e32 v108, v225, v108, vcc
	v_cmp_le_u32_e32 vcc, v2, v138
	v_subrev_u32_e32 v2, 37, v1
	s_nop 0
	v_cndmask_b32_e32 v109, v225, v109, vcc
	v_cmp_le_u32_e32 vcc, v2, v138
	v_subrev_u32_e32 v2, 36, v1
	s_nop 0
	v_cndmask_b32_e32 v110, v225, v110, vcc
	v_cmp_le_u32_e32 vcc, v2, v138
	v_subrev_u32_e32 v2, 31, v1
	s_nop 0
	v_cndmask_b32_e32 v111, v225, v111, vcc
	v_cmp_le_u32_e32 vcc, v2, v138
	v_subrev_u32_e32 v2, 30, v1
	s_nop 0
	v_cndmask_b32_e32 v80, v225, v80, vcc
	v_cmp_le_u32_e32 vcc, v2, v138
	v_subrev_u32_e32 v2, 29, v1
	s_nop 0
	v_cndmask_b32_e32 v81, v225, v81, vcc
	v_cmp_le_u32_e32 vcc, v2, v138
	v_subrev_u32_e32 v2, 28, v1
	s_nop 0
	v_cndmask_b32_e32 v82, v225, v82, vcc
	v_cmp_le_u32_e32 vcc, v2, v138
	v_subrev_u32_e32 v2, 23, v1
	s_nop 0
	v_cndmask_b32_e32 v83, v225, v83, vcc
	v_cmp_le_u32_e32 vcc, v2, v138
	v_subrev_u32_e32 v2, 22, v1
	s_nop 0
	v_cndmask_b32_e32 v84, v225, v84, vcc
	v_cmp_le_u32_e32 vcc, v2, v138
	v_subrev_u32_e32 v2, 21, v1
	s_nop 0
	v_cndmask_b32_e32 v85, v225, v85, vcc
	v_cmp_le_u32_e32 vcc, v2, v138
	v_subrev_u32_e32 v2, 20, v1
	s_nop 0
	v_cndmask_b32_e32 v86, v225, v86, vcc
	v_cmp_le_u32_e32 vcc, v2, v138
	v_add_u32_e32 v2, -15, v1
	s_nop 0
	v_cndmask_b32_e32 v87, v225, v87, vcc
	v_cmp_le_u32_e32 vcc, v2, v138
	v_add_u32_e32 v2, -14, v1
	s_nop 0
	v_cndmask_b32_e32 v88, v225, v88, vcc
	v_cmp_le_u32_e32 vcc, v2, v138
	v_add_u32_e32 v2, -13, v1
	s_nop 0
	v_cndmask_b32_e32 v89, v225, v89, vcc
	v_cmp_le_u32_e32 vcc, v2, v138
	v_add_u32_e32 v2, -12, v1
	s_nop 0
	v_cndmask_b32_e32 v90, v225, v90, vcc
	v_cmp_le_u32_e32 vcc, v2, v138
	v_add_u32_e32 v2, -7, v1
	s_nop 0
	v_cndmask_b32_e32 v91, v225, v91, vcc
	v_cmp_le_u32_e32 vcc, v2, v138
	v_add_u32_e32 v2, -6, v1
	s_nop 0
	v_cndmask_b32_e32 v92, v225, v92, vcc
	v_cmp_le_u32_e32 vcc, v2, v138
	v_add_u32_e32 v2, -5, v1
	v_add_u32_e32 v1, -4, v1
	v_cndmask_b32_e32 v93, v225, v93, vcc
	v_cmp_le_u32_e32 vcc, v2, v138
	s_nop 1
	v_cndmask_b32_e32 v94, v225, v94, vcc
	v_cmp_le_u32_e32 vcc, v1, v138
	s_nop 1
	v_cndmask_b32_e32 v95, v225, v95, vcc
; #define LAS __attribute__((address_space(3)))
; __device__ __forceinline__ unsigned pk2(float lo, float hi) { f32x2_t v = {lo, hi}; bf16x2_t b = __builtin_convertvector(v, bf16x2_t); return __builtin_bit_cast(unsigned, b); }
; template <bool DIFF>
; __device__ __forceinline__ void attn_unit(CA& A, int l, int b, int hh, int qb, LAS unsigned char* lds, float lam, float lam_init) {
;     ...
; #pragma unroll
;             for (int kt = 0; kt < 2; ++kt)
; #pragma unroll
;                 for (int r = 0; r < 16; ++r) p[kt][r] = __builtin_amdgcn_exp2f(p[kt][r]);
;             bf16x8 pb[2][2];
; #pragma unroll
;             for (int kt = 0; kt < 2; ++kt)
; #pragma unroll
;                 for (int i = 0; i < 2; ++i) { v4u w;
; #pragma unroll
;                     for (int j = 0; j < 4; ++j) w[j] = pk2(p[kt][8 * i + 2 * j], p[kt][8 * i + 2 * j + 1]);
;                     pb[kt][i] = __builtin_bit_cast(bf16x8, w); }
; #pragma unroll
;             for (int kt = 0; kt < 2; ++kt)
; #pragma unroll
;                 for (int i = 0; i < 2; ++i) {
; #pragma unroll
;                     for (int dt = 0; dt < 2; ++dt) {
;                         const LAS unsigned char* vq = Vb + (32 * dt + r32) * 136 + (32 * kt + 16 * i + 4 * hi) * 2;
;                         const s16x4 lo = *(const LAS s16x4*)vq, h4 = *(const LAS s16x4*)(vq + 16);
;                         const bf16x8 a = {lo[0], lo[1], lo[2], lo[3], h4[0], h4[1], h4[2], h4[3]};
;                         o[dt] = __builtin_amdgcn_mfma_f32_32x32x16_bf16(a, pb[kt][i], o[dt], 0, 0, 0);
;                     }
;                     ol = __builtin_amdgcn_mfma_f32_32x32x16_bf16(ones, pb[kt][i], ol, 0, 0, 0);
;                 }
;         }
;         if (has_next) ATT_WRITE(buf ^ 1);
; __device__ __forceinline__ void mix_phase(CA& A0, int l, LAS unsigned char* lds) {
;     ...
;     for (;;) {
;         __syncthreads();
;         if (tid == 0) *slot = (int)atomicAdd(counter, 1u);
;         __syncthreads();
;         const int it = *slot;
;         if (it >= MIX_ITEMS) break;
.Lmy_df0_pv:
	v_exp_f32_e32 v96, v96
	v_exp_f32_e32 v97, v97
	v_exp_f32_e32 v98, v98
	v_exp_f32_e32 v99, v99
	v_exp_f32_e32 v100, v100
	v_exp_f32_e32 v101, v101
	v_exp_f32_e32 v102, v102
	v_exp_f32_e32 v103, v103
	v_cvt_pk_bf16_f32 v6, v96, v97
	v_cvt_pk_bf16_f32 v7, v98, v99
	v_cvt_pk_bf16_f32 v8, v100, v101
	v_cvt_pk_bf16_f32 v9, v102, v103
	v_exp_f32_e32 v104, v104
	v_exp_f32_e32 v105, v105
	s_waitcnt lgkmcnt(6)
	v_mfma_f32_32x32x16_bf16 v[32:47], v[164:167], v[6:9], v[32:47]
	v_exp_f32_e32 v106, v106
	v_exp_f32_e32 v107, v107
	v_cvt_pk_bf16_f32 v208, v104, v105
	v_mfma_f32_32x32x16_bf16 v[16:31], v[168:171], v[6:9], v[16:31]
	v_exp_f32_e32 v108, v108
	v_exp_f32_e32 v109, v109
	v_cvt_pk_bf16_f32 v209, v106, v107
	v_mfma_f32_32x32x16_bf16 v[64:79], v[204:207], v[6:9], v[64:79]
	v_exp_f32_e32 v110, v110
	v_exp_f32_e32 v111, v111
	v_cvt_pk_bf16_f32 v210, v108, v109
	v_exp_f32_e32 v80, v80
	v_cvt_pk_bf16_f32 v211, v110, v111
	v_exp_f32_e32 v81, v81
	s_waitcnt lgkmcnt(4)
	v_mfma_f32_32x32x16_bf16 v[32:47], v[172:175], v[208:211], v[32:47]
	v_exp_f32_e32 v82, v82
	v_exp_f32_e32 v83, v83
	v_cvt_pk_bf16_f32 v6, v80, v81
	v_mfma_f32_32x32x16_bf16 v[16:31], v[180:183], v[208:211], v[16:31]
	v_exp_f32_e32 v84, v84
	v_exp_f32_e32 v85, v85
	v_cvt_pk_bf16_f32 v7, v82, v83
	v_mfma_f32_32x32x16_bf16 v[64:79], v[204:207], v[208:211], v[64:79]
	v_exp_f32_e32 v86, v86
	v_exp_f32_e32 v87, v87
	v_cvt_pk_bf16_f32 v8, v84, v85
	v_exp_f32_e32 v88, v88
	v_cvt_pk_bf16_f32 v9, v86, v87
	v_exp_f32_e32 v89, v89
	s_waitcnt lgkmcnt(2)
	v_mfma_f32_32x32x16_bf16 v[32:47], v[184:187], v[6:9], v[32:47]
	v_exp_f32_e32 v90, v90
	v_exp_f32_e32 v91, v91
	v_cvt_pk_bf16_f32 v208, v88, v89
	v_mfma_f32_32x32x16_bf16 v[16:31], v[188:191], v[6:9], v[16:31]
	v_exp_f32_e32 v92, v92
	v_exp_f32_e32 v93, v93
	v_cvt_pk_bf16_f32 v209, v90, v91
	v_mfma_f32_32x32x16_bf16 v[64:79], v[204:207], v[6:9], v[64:79]
	v_exp_f32_e32 v94, v94
	v_exp_f32_e32 v95, v95
	v_cvt_pk_bf16_f32 v210, v92, v93
	s_nop 0
	v_cvt_pk_bf16_f32 v211, v94, v95
	s_waitcnt lgkmcnt(0)
	s_nop 0
	v_mfma_f32_32x32x16_bf16 v[32:47], v[192:195], v[208:211], v[32:47]
	v_mfma_f32_32x32x16_bf16 v[16:31], v[196:199], v[208:211], v[16:31]
	v_mfma_f32_32x32x16_bf16 v[64:79], v[204:207], v[208:211], v[64:79]
	s_waitcnt vmcnt(0)
	ds_write_b128 v139, v[120:123] offset:9216
	ds_write_b16 v140, v124 offset:27136
	ds_write_b16_d16_hi v140, v124 offset:27272
	ds_write_b16 v140, v125 offset:27408
	ds_write_b16_d16_hi v140, v125 offset:27544
	ds_write_b16 v140, v126 offset:27680
	ds_write_b16_d16_hi v140, v126 offset:27816
	ds_write_b16 v140, v127 offset:27952
	ds_write_b16_d16_hi v140, v127 offset:28088
	s_mov_b64 s[38:39], exec
	v_readlane_b32 s40, v236, 5
	v_readlane_b32 s41, v236, 6
	s_nop 1
	s_and_b64 s[40:41], s[38:39], s[40:41]
	s_mov_b64 exec, s[40:41]
	s_cbranch_execz .Lmy_pf_diff_x
	v_readlane_b32 s40, v236, 3
	v_readlane_b32 s41, v236, 4
	v_mov_b32_e32 v239, 1
	s_nop 4
	global_atomic_add v239, v0, v239, s[40:41] sc0
; #define LAS __attribute__((address_space(3)))
; __device__ __forceinline__ int crow(int r, int hi) { return (r & 3) + 8 * (r >> 2) + 4 * hi; }
; #define ATT_LOAD(t) do { kraw = *(const v4u*)(kp + (size_t)(t) * 64 * ZC); vraw = *(const v4u*)(vp + (size_t)(t) * 64 * ZC); \
;         if (!DIFF && tid < 64) ncv = ncp[(t) * 64 + tid]; } while (0)
; template <bool DIFF>
; __device__ __forceinline__ void attn_unit(CA& A, int l, int b, int hh, int qb, LAS unsigned char* lds, float lam, float lam_init) {
;     ...
;         if (has_next) { ATT_LOAD(DIFF ? t + 1 : t - 1); if (!DIFF) nc_hi = ncp[key0 - 1]; }
;         if (key0 <= qlast) {
;             const LAS unsigned char* Kb = lds + AL_KS + buf * AL_KSZ;
;             const LAS unsigned char* Vb = lds + AL_VT + buf * AL_VSZ;
;             f32x16 p[2];
; #pragma unroll
;             for (int kt = 0; kt < 2; ++kt) {
;                 if (!DIFF) {
;                     const LAS float* nc = (const LAS float*)(lds + AL_NC + buf * 512) + 32 * kt + 4 * hi;
; #pragma unroll
;                     for (int g = 0; g < 4; ++g) { const f32x4 c4 = *(const LAS f32x4*)(nc + 8 * g); p[kt][4 * g] = c4[0]; p[kt][4 * g + 1] = c4[1]; p[kt][4 * g + 2] = c4[2]; p[kt][4 * g + 3] = c4[3]; }
;                 }
; #pragma unroll
;                 for (int s = 0; s < NS; ++s) {
;                     const bf16x8 a = *(const LAS bf16x8*)(Kb + (32 * kt + r32) * 144 + (koff + 16 * s + 8 * hi) * 2);
;                     if (DIFF && s == 0) p[kt] = __builtin_amdgcn_mfma_f32_32x32x16_bf16(a, qf[s], negm, 0, 0, 0);
;                     else p[kt] = __builtin_amdgcn_mfma_f32_32x32x16_bf16(a, qf[s], p[kt], 0, 0, 0);
;                 }
;             }
;             if (!DIFF) {
; #pragma unroll
;                 for (int kt = 0; kt < 2; ++kt)
; #pragma unroll
;                     for (int r = 0; r < 16; ++r) p[kt][r] -= m_ref;
;             }
;             if (key0 + 63 > qfirst) {
; #pragma unroll
;                 for (int kt = 0; kt < 2; ++kt)
; #pragma unroll
;                     for (int r = 0; r < 16; ++r) if (key0 + 32 * kt + crow(r, hi) > qmine) p[kt][r] = -1e30f;
;             }
.Lmy_pf_diff_x:
	s_mov_b64 exec, s[38:39]
	s_add_i32 s26, s26, 64
	s_waitcnt lgkmcnt(0)
	s_barrier
	s_sub_i32 s30, s26, 63
	s_cmp_gt_u32 s30, s28
	s_cbranch_scc1 .Lmy_df_skip
	ds_read_b128 v[148:151], v200 offset:9216
	ds_read_b128 v[152:155], v201 offset:9216
	ds_read_b128 v[156:159], v200 offset:9248
	ds_read_b128 v[160:163], v201 offset:9248
	s_waitcnt lgkmcnt(2)
	v_mfma_f32_32x32x16_bf16 v[96:111], v[148:151], v[112:115], v[48:63]
	v_mfma_f32_32x32x16_bf16 v[80:95], v[152:155], v[112:115], v[48:63]
	s_waitcnt lgkmcnt(0)
	v_mfma_f32_32x32x16_bf16 v[96:111], v[156:159], v[116:119], v[96:111]
	v_mfma_f32_32x32x16_bf16 v[80:95], v[160:163], v[116:119], v[80:95]
	ds_read2_b64 v[164:167], v212 offset0:0 offset1:2
	ds_read2_b64 v[168:171], v213 offset0:32 offset1:34
	ds_read2_b64 v[172:175], v212 offset0:4 offset1:6
	ds_read2_b64 v[180:183], v213 offset0:36 offset1:38
	ds_read2_b64 v[184:187], v212 offset0:8 offset1:10
	ds_read2_b64 v[188:191], v213 offset0:40 offset1:42
	ds_read2_b64 v[192:195], v212 offset0:12 offset1:14
	ds_read2_b64 v[196:199], v213 offset0:44 offset1:46
	s_cmp_le_u32 s26, s25
	s_nop 1
	s_cbranch_scc1 .Lmy_df1_pv
	v_add_u32_e32 v1, s26, v131
	v_subrev_u32_e32 v2, 63, v1
	v_cmp_gt_u32_e32 vcc, v2, v138
	s_nop 1
	v_cndmask_b32_e32 v3, v96, v225, vcc
	v_cmp_lt_u32_e32 vcc, v2, v138
	v_subrev_u32_e32 v2, 61, v1
	s_nop 0
	v_cndmask_b32_e32 v96, v3, v96, vcc
	v_cndmask_b32_e32 v97, v225, v97, vcc
	v_cmp_le_u32_e32 vcc, v2, v138
	v_subrev_u32_e32 v2, 60, v1
	s_nop 0
	v_cndmask_b32_e32 v98, v225, v98, vcc
	v_cmp_le_u32_e32 vcc, v2, v138
	v_subrev_u32_e32 v2, 55, v1
	s_nop 0
	v_cndmask_b32_e32 v99, v225, v99, vcc
	v_cmp_le_u32_e32 vcc, v2, v138
	v_subrev_u32_e32 v2, 54, v1
	s_nop 0
	v_cndmask_b32_e32 v100, v225, v100, vcc
	v_cmp_le_u32_e32 vcc, v2, v138
	v_subrev_u32_e32 v2, 53, v1
	s_nop 0
	v_cndmask_b32_e32 v101, v225, v101, vcc
	v_cmp_le_u32_e32 vcc, v2, v138
	v_subrev_u32_e32 v2, 52, v1
	s_nop 0
	v_cndmask_b32_e32 v102, v225, v102, vcc
	v_cmp_le_u32_e32 vcc, v2, v138
	v_subrev_u32_e32 v2, 47, v1
	s_nop 0
	v_cndmask_b32_e32 v103, v225, v103, vcc
	v_cmp_le_u32_e32 vcc, v2, v138
	v_subrev_u32_e32 v2, 46, v1
	s_nop 0
	v_cndmask_b32_e32 v104, v225, v104, vcc
	v_cmp_le_u32_e32 vcc, v2, v138
	v_subrev_u32_e32 v2, 45, v1
	s_nop 0
	v_cndmask_b32_e32 v105, v225, v105, vcc
	v_cmp_le_u32_e32 vcc, v2, v138
	v_subrev_u32_e32 v2, 44, v1
	s_nop 0
	v_cndmask_b32_e32 v106, v225, v106, vcc
	v_cmp_le_u32_e32 vcc, v2, v138
	v_subrev_u32_e32 v2, 39, v1
	s_nop 0
	v_cndmask_b32_e32 v107, v225, v107, vcc
	v_cmp_le_u32_e32 vcc, v2, v138
	v_subrev_u32_e32 v2, 38, v1
	s_nop 0
	v_cndmask_b32_e32 v108, v225, v108, vcc
	v_cmp_le_u32_e32 vcc, v2, v138
	v_subrev_u32_e32 v2, 37, v1
	s_nop 0
	v_cndmask_b32_e32 v109, v225, v109, vcc
	v_cmp_le_u32_e32 vcc, v2, v138
	v_subrev_u32_e32 v2, 36, v1
	s_nop 0
	v_cndmask_b32_e32 v110, v225, v110, vcc
	v_cmp_le_u32_e32 vcc, v2, v138
	v_subrev_u32_e32 v2, 31, v1
	s_nop 0
	v_cndmask_b32_e32 v111, v225, v111, vcc
	v_cmp_le_u32_e32 vcc, v2, v138
	v_subrev_u32_e32 v2, 30, v1
	s_nop 0
	v_cndmask_b32_e32 v80, v225, v80, vcc
	v_cmp_le_u32_e32 vcc, v2, v138
	v_subrev_u32_e32 v2, 29, v1
	s_nop 0
	v_cndmask_b32_e32 v81, v225, v81, vcc
	v_cmp_le_u32_e32 vcc, v2, v138
	v_subrev_u32_e32 v2, 28, v1
	s_nop 0
	v_cndmask_b32_e32 v82, v225, v82, vcc
	v_cmp_le_u32_e32 vcc, v2, v138
	v_subrev_u32_e32 v2, 23, v1
	s_nop 0
	v_cndmask_b32_e32 v83, v225, v83, vcc
	v_cmp_le_u32_e32 vcc, v2, v138
	v_subrev_u32_e32 v2, 22, v1
	s_nop 0
	v_cndmask_b32_e32 v84, v225, v84, vcc
	v_cmp_le_u32_e32 vcc, v2, v138
	v_subrev_u32_e32 v2, 21, v1
	s_nop 0
	v_cndmask_b32_e32 v85, v225, v85, vcc
	v_cmp_le_u32_e32 vcc, v2, v138
	v_subrev_u32_e32 v2, 20, v1
	s_nop 0
	v_cndmask_b32_e32 v86, v225, v86, vcc
	v_cmp_le_u32_e32 vcc, v2, v138
	v_add_u32_e32 v2, -15, v1
	s_nop 0
	v_cndmask_b32_e32 v87, v225, v87, vcc
	v_cmp_le_u32_e32 vcc, v2, v138
	v_add_u32_e32 v2, -14, v1
	s_nop 0
	v_cndmask_b32_e32 v88, v225, v88, vcc
	v_cmp_le_u32_e32 vcc, v2, v138
	v_add_u32_e32 v2, -13, v1
	s_nop 0
	v_cndmask_b32_e32 v89, v225, v89, vcc
	v_cmp_le_u32_e32 vcc, v2, v138
	v_add_u32_e32 v2, -12, v1
	s_nop 0
	v_cndmask_b32_e32 v90, v225, v90, vcc
	v_cmp_le_u32_e32 vcc, v2, v138
	v_add_u32_e32 v2, -7, v1
	s_nop 0
	v_cndmask_b32_e32 v91, v225, v91, vcc
	v_cmp_le_u32_e32 vcc, v2, v138
	v_add_u32_e32 v2, -6, v1
	s_nop 0
	v_cndmask_b32_e32 v92, v225, v92, vcc
	v_cmp_le_u32_e32 vcc, v2, v138
	v_add_u32_e32 v2, -5, v1
	v_add_u32_e32 v1, -4, v1
	v_cndmask_b32_e32 v93, v225, v93, vcc
	v_cmp_le_u32_e32 vcc, v2, v138
	s_nop 1
	v_cndmask_b32_e32 v94, v225, v94, vcc
	v_cmp_le_u32_e32 vcc, v1, v138
	s_nop 1
	v_cndmask_b32_e32 v95, v225, v95, vcc
